# PEER q staging: bf16 conversions packed pairwise (one v_cvt_pk per two values, low half ds_write_b16 + high half ds_write_b16_d16_hi), 32 fewer VALU per iteration
# baseline (speedup 1.0000x reference)
; DEV f32x16 mfma32(bf16x8 a, bf16x8 b, f32x16 c) { return __builtin_amdgcn_mfma_f32_32x32x16_bf16(a, b, c, 0, 0, 0); }
; DEV void gemm_core(const bf16_t* __restrict__ A, const bf16_t* __restrict__ Bt, int m0, int n0, bf16_t* As, bf16_t* Bs, int tid,
;                    f32x16 (&acc)[2][2]) {
;   const int lane = tid & 63, w = tid >> 6;
;   const int wm = w >> 1, wn = w & 1, lr = lane & 31, hk = lane >> 5;
; #pragma unroll
;   for (int a = 0; a < 2; ++a)
; #pragma unroll
;     for (int b = 0; b < 2; ++b)
; #pragma unroll
;       for (int i = 0; i < 16; ++i) acc[a][b][i] = 0.f;
;   uint4 ra0, ra1, ra2, ra3, rb0, rb1, rb2, rb3;
;   const int lrow = tid >> 3, lc8 = (tid & 7) * 8;
;   const bf16_t* Ap = A + (size_t)(m0 + lrow) * 1024 + lc8;
;   const bf16_t* Bp = Bt + (size_t)(n0 + lrow) * 1024 + lc8;
;     ...
;   GLOAD(0);
;   for (int kt = 0; kt < 16; ++kt) {
;     __syncthreads();
;     {
;       bf16_t* as = As + lrow * 72 + lc8; bf16_t* bs = Bs + lrow * 72 + lc8;
;       *(uint4*)(as) = ra0; *(uint4*)(as + 32 * 72) = ra1; *(uint4*)(as + 64 * 72) = ra2; *(uint4*)(as + 96 * 72) = ra3;
;       *(uint4*)(bs) = rb0; *(uint4*)(bs + 32 * 72) = rb1; *(uint4*)(bs + 64 * 72) = rb2; *(uint4*)(bs + 96 * 72) = rb3;
;     }
;     __syncthreads();
;     {
;       const int k0 = (kt + 1 < 16) ? (kt + 1) * 64 : 15 * 64;
;       GLOAD(k0);
;     }
; #pragma unroll
;     for (int kk = 0; kk < 4; ++kk) {
;       bf16x8 af[2], bfr[2];
; #pragma unroll
;       for (int mi = 0; mi < 2; ++mi) af[mi] = *(const bf16x8*)(As + (wm * 64 + mi * 32 + lr) * 72 + kk * 16 + hk * 8);
; #pragma unroll
;       for (int ni = 0; ni < 2; ++ni) bfr[ni] = *(const bf16x8*)(Bs + (wn * 64 + ni * 32 + lr) * 72 + kk * 16 + hk * 8);
; #pragma unroll
;       for (int mi = 0; mi < 2; ++mi)
; #pragma unroll
;         for (int ni = 0; ni < 2; ++ni) acc[mi][ni] = mfma32(af[mi], bfr[ni], acc[mi][ni]);
;     }
;   }
;     ...
; }
.LBB0_46:
	s_barrier
	s_waitcnt vmcnt(6)
	ds_write_b128 v98, v[68:71]
	s_waitcnt vmcnt(5)
	ds_write_b128 v98, v[72:75] offset:4608
	s_waitcnt vmcnt(4)
	ds_write_b128 v98, v[76:79] offset:9216
	s_waitcnt vmcnt(3)
	ds_write_b128 v98, v[80:83] offset:13824
	s_waitcnt vmcnt(3)
	ds_write_b128 v98, v[64:67] offset:18432
	s_waitcnt vmcnt(2)
	ds_write_b128 v98, v[84:87] offset:23040
	s_waitcnt vmcnt(1)
	ds_write_b128 v98, v[88:91] offset:27648
	s_waitcnt vmcnt(0)
	ds_write_b128 v98, v[92:95] offset:32256
	s_waitcnt lgkmcnt(0)
	s_barrier
	ds_read_b128 v[64:67], v189
	ds_read_b128 v[68:71], v190 offset:18432
	ds_read_b128 v[72:75], v189 offset:32
	ds_read_b128 v[76:79], v190 offset:18464
	ds_read_b128 v[80:83], v190 offset:23040
	ds_read_b128 v[84:87], v190 offset:23072
	s_waitcnt lgkmcnt(4)
	v_mfma_f32_32x32x16_bf16 v[48:63], v[64:67], v[68:71], v[48:63]
	s_waitcnt lgkmcnt(1)
	v_mfma_f32_32x32x16_bf16 v[32:47], v[64:67], v[80:83], v[32:47]
	ds_read_b128 v[64:67], v189 offset:4608
	ds_read_b128 v[88:91], v189 offset:4640
	s_waitcnt lgkmcnt(1)
	v_mfma_f32_32x32x16_bf16 v[16:31], v[64:67], v[68:71], v[16:31]
	v_mfma_f32_32x32x16_bf16 v[48:63], v[72:75], v[76:79], v[48:63]
	v_mfma_f32_32x32x16_bf16 v[32:47], v[72:75], v[84:87], v[32:47]
	v_mfma_f32_32x32x16_bf16 v[0:15], v[64:67], v[80:83], v[0:15]
	ds_read_b128 v[64:67], v189 offset:64
	ds_read_b128 v[68:71], v190 offset:18496
	ds_read_b128 v[72:75], v189 offset:96
	ds_read_b128 v[92:95], v190 offset:18528
	v_lshl_add_u64 v[80:81], v[148:149], 0, s[38:39]
	v_lshl_add_u64 v[82:83], v[150:151], 0, s[38:39]
	s_add_u32 s38, s38, 0x80
	s_addc_u32 s39, s39, 0
	s_cmpk_lg_i32 s38, 0x780
	s_waitcnt lgkmcnt(4)
	v_mfma_f32_32x32x16_bf16 v[16:31], v[88:91], v[76:79], v[16:31]
	ds_read_b128 v[76:79], v190 offset:23104
	ds_read_b128 v[192:195], v190 offset:23136
	ds_read_b128 v[196:199], v189 offset:4704
	s_waitcnt lgkmcnt(5)
	v_mfma_f32_32x32x16_bf16 v[48:63], v[64:67], v[68:71], v[48:63]
	s_waitcnt lgkmcnt(2)
	v_mfma_f32_32x32x16_bf16 v[32:47], v[64:67], v[76:79], v[32:47]
	ds_read_b128 v[64:67], v189 offset:4672
	v_mfma_f32_32x32x16_bf16 v[0:15], v[88:91], v[84:87], v[0:15]
	v_add_co_u32_e32 v84, vcc, s42, v80
	s_nop 1
	v_addc_co_u32_e32 v85, vcc, 0, v81, vcc
	v_add_co_u32_e32 v86, vcc, s43, v80
	s_waitcnt lgkmcnt(0)
	v_mfma_f32_32x32x16_bf16 v[16:31], v[64:67], v[68:71], v[16:31]
	v_addc_co_u32_e32 v87, vcc, 0, v81, vcc
	v_add_co_u32_e32 v88, vcc, s44, v80
	s_nop 1
	v_addc_co_u32_e32 v89, vcc, 0, v81, vcc
	v_add_co_u32_e32 v90, vcc, s42, v82
	v_mfma_f32_32x32x16_bf16 v[0:15], v[64:67], v[76:79], v[0:15]
	s_nop 0
	v_addc_co_u32_e32 v91, vcc, 0, v83, vcc
	v_add_co_u32_e32 v200, vcc, s43, v82
	global_load_dwordx4 v[64:67], v[82:83], off offset:128
	s_nop 0
	v_addc_co_u32_e32 v201, vcc, 0, v83, vcc
	v_add_co_u32_e32 v228, vcc, s44, v82
	v_mfma_f32_32x32x16_bf16 v[48:63], v[72:75], v[92:95], v[48:63]
	s_nop 0
	v_addc_co_u32_e32 v229, vcc, 0, v83, vcc
	v_mfma_f32_32x32x16_bf16 v[32:47], v[72:75], v[192:195], v[32:47]
	global_load_dwordx4 v[68:71], v[80:81], off offset:128
	global_load_dwordx4 v[72:75], v[84:85], off offset:128
	global_load_dwordx4 v[76:79], v[86:87], off offset:128
	s_nop 0
	global_load_dwordx4 v[80:83], v[88:89], off offset:128
	global_load_dwordx4 v[84:87], v[90:91], off offset:128
	s_nop 0
	global_load_dwordx4 v[88:91], v[200:201], off offset:128
	v_mfma_f32_32x32x16_bf16 v[16:31], v[196:199], v[92:95], v[16:31]
	global_load_dwordx4 v[92:95], v[228:229], off offset:128
	v_mfma_f32_32x32x16_bf16 v[0:15], v[196:199], v[192:195], v[0:15]
	s_cbranch_scc1 .LBB0_46
	s_barrier
	s_waitcnt vmcnt(6)
	ds_write_b128 v98, v[68:71]
	s_waitcnt vmcnt(5)
	ds_write_b128 v98, v[72:75] offset:4608
	s_waitcnt vmcnt(4)
	ds_write_b128 v98, v[76:79] offset:9216
	s_waitcnt vmcnt(3)
	ds_write_b128 v98, v[80:83] offset:13824
	ds_write_b128 v98, v[64:67] offset:18432
	s_waitcnt vmcnt(2)
	ds_write_b128 v98, v[84:87] offset:23040
	s_waitcnt vmcnt(1)
	ds_write_b128 v98, v[88:91] offset:27648
	s_waitcnt vmcnt(0)
	ds_write_b128 v98, v[92:95] offset:32256
	s_waitcnt lgkmcnt(0)
	s_barrier
	ds_read_b128 v[64:67], v189 offset:4608
	ds_read_b128 v[68:71], v190 offset:23040
	ds_read_b128 v[72:75], v189
	ds_read_b128 v[76:79], v189 offset:32
	ds_read_b128 v[80:83], v190 offset:18432
	ds_read_b128 v[84:87], v190 offset:18464
	s_waitcnt lgkmcnt(1)
	v_mfma_f32_32x32x16_bf16 v[48:63], v[72:75], v[80:83], v[48:63]
	v_readlane_b32 s38, v249, 58
	s_or_b32 s38, s41, s38
	s_ashr_i32 s39, s38, 31
	s_lshl_b64 s[38:39], s[38:39], 8
	s_movk_i32 s41, 0x80
	v_mfma_f32_32x32x16_bf16 v[32:47], v[72:75], v[68:71], v[32:47]
	v_mfma_f32_32x32x16_bf16 v[16:31], v[64:67], v[80:83], v[16:31]
	v_mfma_f32_32x32x16_bf16 v[0:15], v[64:67], v[68:71], v[0:15]
	ds_read_b128 v[64:67], v189 offset:4640
	ds_read_b128 v[68:71], v190 offset:23072
	s_waitcnt lgkmcnt(2)
	v_mfma_f32_32x32x16_bf16 v[48:63], v[76:79], v[84:87], v[48:63]
	s_waitcnt lgkmcnt(0)
	v_mfma_f32_32x32x16_bf16 v[32:47], v[76:79], v[68:71], v[32:47]
	v_mfma_f32_32x32x16_bf16 v[16:31], v[64:67], v[84:87], v[16:31]
	v_mfma_f32_32x32x16_bf16 v[0:15], v[64:67], v[68:71], v[0:15]
	ds_read_b128 v[64:67], v189 offset:64
	ds_read_b128 v[68:71], v189 offset:4672
	ds_read_b128 v[72:75], v190 offset:18496
	ds_read_b128 v[76:79], v190 offset:23104
	s_waitcnt lgkmcnt(1)
	v_mfma_f32_32x32x16_bf16 v[48:63], v[64:67], v[72:75], v[48:63]
	s_waitcnt lgkmcnt(0)
	v_mfma_f32_32x32x16_bf16 v[32:47], v[64:67], v[76:79], v[32:47]
	v_mfma_f32_32x32x16_bf16 v[16:31], v[68:71], v[72:75], v[16:31]
	v_mfma_f32_32x32x16_bf16 v[0:15], v[68:71], v[76:79], v[0:15]
	ds_read_b128 v[64:67], v189 offset:96
	ds_read_b128 v[68:71], v189 offset:4704
	ds_read_b128 v[72:75], v190 offset:18528
	ds_read_b128 v[76:79], v190 offset:23136
	s_waitcnt lgkmcnt(1)
; DEV unsigned short f2bf(float f) { return (unsigned short)(pack2(f, 0.f) & 0xFFFFu); }
; __device__ void peer_q_topk_item(const Params& P, int l, int item, char* smem) {
;     ...
; #pragma unroll
;       for (int mi = 0; mi < 2; ++mi)
; #pragma unroll
;         for (int ni = 0; ni < 2; ++ni) {
;           const int col = wn * 64 + ni * 32 + lr;
;           const int rbase = wm * 64 + mi * 32 + 4 * hk;
; #pragma unroll
;           for (int i = 0; i < 16; ++i) Qs[(rbase + (i & 3) + 8 * (i >> 2)) * 136 + col] = f2bf(acc[mi][ni][i]);
;         }
;     }
;     __syncthreads();
;     {
;       const bf16_t* skg = P.SK + (size_t)((l * 2 + c) * 128) * 128;
; #pragma unroll
;       for (int k = 0; k < 8; ++k) {
;         const int ch = tid + 256 * k;
;         const int row = ch >> 4, c8 = (ch & 15) * 8;
;         *(uint4*)(As + row * 136 + c8) = *(const uint4*)(skg + row * 128 + c8);
;       }
;     }
	v_mfma_f32_32x32x16_bf16 v[48:63], v[64:67], v[72:75], v[48:63]
	s_waitcnt lgkmcnt(0)
	v_mfma_f32_32x32x16_bf16 v[32:47], v[64:67], v[76:79], v[32:47]
	s_nop 9
	v_cvt_pk_bf16_f32 v48, v48, v49
	ds_write_b16 v102, v48 offset:36864
	ds_write_b16_d16_hi v183, v48 offset:36864
	v_cvt_pk_bf16_f32 v48, v50, v51
	ds_write_b16 v184, v48 offset:36864
	ds_write_b16_d16_hi v185, v48 offset:36864
	v_cvt_pk_bf16_f32 v48, v52, v53
	ds_write_b16 v186, v48 offset:36864
	ds_write_b16_d16_hi v102, v48 offset:39312
	v_cvt_pk_bf16_f32 v48, v54, v55
	ds_write_b16 v102, v48 offset:39584
	ds_write_b16_d16_hi v102, v48 offset:39856
	v_cvt_pk_bf16_f32 v48, v56, v57
	ds_write_b16 v187, v48 offset:36864
	ds_write_b16_d16_hi v102, v48 offset:41488
	v_cvt_pk_bf16_f32 v48, v58, v59
	ds_write_b16 v102, v48 offset:41760
	ds_write_b16_d16_hi v102, v48 offset:42032
	v_cvt_pk_bf16_f32 v48, v60, v61
	ds_write_b16 v188, v48 offset:36864
	ds_write_b16_d16_hi v102, v48 offset:43664
	v_cvt_pk_bf16_f32 v48, v62, v63
	v_cvt_pk_bf16_f32 v32, v32, v33
	ds_write_b16 v102, v48 offset:43936
	ds_write_b16_d16_hi v102, v48 offset:44208
	ds_write_b16 v102, v32 offset:36928
	ds_write_b16_d16_hi v183, v32 offset:36928
	v_cvt_pk_bf16_f32 v32, v34, v35
	v_mfma_f32_32x32x16_bf16 v[0:15], v[68:71], v[76:79], v[0:15]
	ds_write_b16 v184, v32 offset:36928
	ds_write_b16_d16_hi v185, v32 offset:36928
	v_cvt_pk_bf16_f32 v32, v36, v37
	ds_write_b16 v186, v32 offset:36928
	ds_write_b16_d16_hi v102, v32 offset:39376
	v_mfma_f32_32x32x16_bf16 v[16:31], v[68:71], v[72:75], v[16:31]
	v_cvt_pk_bf16_f32 v32, v38, v39
	ds_write_b16 v102, v32 offset:39648
	ds_write_b16_d16_hi v102, v32 offset:39920
	v_cvt_pk_bf16_f32 v32, v40, v41
	ds_write_b16 v187, v32 offset:36928
	ds_write_b16_d16_hi v102, v32 offset:41552
	v_cvt_pk_bf16_f32 v32, v42, v43
	ds_write_b16 v102, v32 offset:41824
	ds_write_b16_d16_hi v102, v32 offset:42096
	s_nop 3
	v_cvt_pk_bf16_f32 v0, v0, v1
	v_cvt_pk_bf16_f32 v16, v16, v17
	ds_write_b16 v102, v0 offset:45632
	ds_write_b16_d16_hi v102, v0 offset:45904
	ds_write_b16 v102, v16 offset:45568
	ds_write_b16_d16_hi v102, v16 offset:45840
	v_cvt_pk_bf16_f32 v0, v2, v3
	v_cvt_pk_bf16_f32 v16, v18, v19
	ds_write_b16 v102, v0 offset:46176
	ds_write_b16_d16_hi v102, v0 offset:46448
	ds_write_b16 v102, v16 offset:46112
	ds_write_b16_d16_hi v102, v16 offset:46384
	v_cvt_pk_bf16_f32 v0, v4, v5
	v_cvt_pk_bf16_f32 v16, v20, v21
	ds_write_b16 v102, v0 offset:47808
	ds_write_b16_d16_hi v102, v0 offset:48080
	ds_write_b16 v102, v16 offset:47744
	ds_write_b16_d16_hi v102, v16 offset:48016
	v_cvt_pk_bf16_f32 v0, v6, v7
	v_cvt_pk_bf16_f32 v16, v22, v23
	ds_write_b16 v102, v0 offset:48352
	ds_write_b16_d16_hi v102, v0 offset:48624
	ds_write_b16 v102, v16 offset:48288
	ds_write_b16_d16_hi v102, v16 offset:48560
	v_cvt_pk_bf16_f32 v0, v8, v9
	v_cvt_pk_bf16_f32 v16, v24, v25
	ds_write_b16 v102, v0 offset:49984
	ds_write_b16_d16_hi v102, v0 offset:50256
	ds_write_b16 v102, v16 offset:49920
	ds_write_b16_d16_hi v102, v16 offset:50192
	v_cvt_pk_bf16_f32 v0, v10, v11
	v_cvt_pk_bf16_f32 v16, v26, v27
	ds_write_b16 v102, v0 offset:50528
	ds_write_b16_d16_hi v102, v0 offset:50800
	ds_write_b16 v102, v16 offset:50464
	ds_write_b16_d16_hi v102, v16 offset:50736
	v_cvt_pk_bf16_f32 v0, v12, v13
	v_cvt_pk_bf16_f32 v32, v44, v45
	v_cvt_pk_bf16_f32 v16, v28, v29
	ds_write_b16 v102, v0 offset:52160
	ds_write_b16_d16_hi v102, v0 offset:52432
	ds_write_b16 v188, v32 offset:36928
	ds_write_b16_d16_hi v102, v32 offset:43728
	ds_write_b16 v102, v16 offset:52096
	ds_write_b16_d16_hi v102, v16 offset:52368
	v_cvt_pk_bf16_f32 v0, v14, v15
	v_lshl_add_u64 v[4:5], v[146:147], 0, s[38:39]
	v_cvt_pk_bf16_f32 v32, v46, v47
	v_cvt_pk_bf16_f32 v16, v30, v31
	ds_write_b16 v102, v0 offset:52704
	ds_write_b16_d16_hi v102, v0 offset:52976
	v_lshl_add_u64 v[0:1], v[104:105], 1, v[4:5]
	ds_write_b16 v102, v32 offset:44000
	ds_write_b16_d16_hi v102, v32 offset:44272
	ds_write_b16 v102, v16 offset:52640
	ds_write_b16_d16_hi v102, v16 offset:52912
	global_load_dwordx4 v[64:67], v[0:1], off
	v_lshl_add_u64 v[0:1], v[108:109], 1, v[4:5]
	global_load_dwordx4 v[68:71], v[0:1], off
	v_lshl_add_u64 v[0:1], v[112:113], 1, v[4:5]
	global_load_dwordx4 v[72:75], v[0:1], off
	v_lshl_add_u64 v[0:1], v[116:117], 1, v[4:5]
	global_load_dwordx4 v[76:79], v[0:1], off
	v_lshl_add_u64 v[0:1], v[120:121], 1, v[4:5]
	global_load_dwordx4 v[80:83], v[0:1], off
	v_lshl_add_u64 v[0:1], v[124:125], 1, v[4:5]
	global_load_dwordx4 v[84:87], v[0:1], off
	v_lshl_add_u64 v[0:1], v[128:129], 1, v[4:5]
	global_load_dwordx4 v[88:91], v[0:1], off
	v_lshl_add_u64 v[0:1], v[132:133], 1, v[4:5]
	global_load_dwordx4 v[92:95], v[0:1], off
	s_waitcnt lgkmcnt(0)
	s_barrier
	s_movk_i32 s39, 0x7f
	s_movk_i32 s38, 0x5f
	s_waitcnt vmcnt(7)
	ds_write_b128 v106, v[64:67]
	s_waitcnt vmcnt(6)
	ds_write_b128 v110, v[68:71]
	s_waitcnt vmcnt(5)
	ds_write_b128 v114, v[72:75]
	s_waitcnt vmcnt(4)
	ds_write_b128 v118, v[76:79]
	s_waitcnt vmcnt(3)
	ds_write_b128 v122, v[80:83]
	s_waitcnt vmcnt(2)
	ds_write_b128 v126, v[84:87]
	s_waitcnt vmcnt(1)
	ds_write_b128 v130, v[88:91]
	s_waitcnt vmcnt(0)
	ds_write_b128 v134, v[92:95]
	s_waitcnt lgkmcnt(0)
	s_barrier
; DEV f32x16 mfma32(bf16x8 a, bf16x8 b, f32x16 c) { return __builtin_amdgcn_mfma_f32_32x32x16_bf16(a, b, c, 0, 0, 0); }
; __device__ void peer_q_topk_item(const Params& P, int l, int item, char* smem) {
;     ...
;     {
;       f32x16 sa[4];
; #pragma unroll
;       for (int m4 = 0; m4 < 4; ++m4)
; #pragma unroll
;         for (int i = 0; i < 16; ++i) sa[m4][i] = 0.f;
;       const bf16_t* qrow = Qs + (w * 32 + q) * 136 + hk * 8;
;       const bf16_t* sk = As + q * 136 + hk * 8;
; #pragma unroll
;       for (int ks = 0; ks < 8; ++ks) {
;         const bf16x8 bq = *(const bf16x8*)(qrow + ks * 16);
; #pragma unroll
;         for (int m4 = 0; m4 < 4; ++m4) {
;           const bf16x8 a = *(const bf16x8*)(sk + (m4 * 32) * 136 + ks * 16);
;           sa[m4] = mfma32(a, bq, sa[m4]);
;         }
;       }
	ds_read_b128 v[0:3], v100 offset:36864
	ds_read_b128 v[64:67], v100 offset:36896
	ds_read_b128 v[4:7], v160
	ds_read_b128 v[68:71], v160 offset:32
	s_waitcnt lgkmcnt(1)
	v_mfma_f32_32x32x16_bf16 v[48:63], v[4:7], v[0:3], 0
	ds_read_b128 v[4:7], v160 offset:8704
	s_waitcnt lgkmcnt(1)
	v_mfma_f32_32x32x16_bf16 v[48:63], v[68:71], v[64:67], v[48:63]
	ds_read_b128 v[68:71], v160 offset:8736
	s_waitcnt lgkmcnt(1)
	v_mfma_f32_32x32x16_bf16 v[32:47], v[4:7], v[0:3], 0
	ds_read_b128 v[4:7], v160 offset:17408
	s_waitcnt lgkmcnt(1)
	v_mfma_f32_32x32x16_bf16 v[32:47], v[68:71], v[64:67], v[32:47]
	ds_read_b128 v[68:71], v160 offset:17440
	s_waitcnt lgkmcnt(1)
	v_mfma_f32_32x32x16_bf16 v[16:31], v[4:7], v[0:3], 0
	ds_read_b128 v[4:7], v160 offset:26112
	s_waitcnt lgkmcnt(1)
	v_mfma_f32_32x32x16_bf16 v[16:31], v[68:71], v[64:67], v[16:31]
	ds_read_b128 v[68:71], v160 offset:26144
	s_waitcnt lgkmcnt(1)
	v_mfma_f32_32x32x16_bf16 v[0:15], v[4:7], v[0:3], 0
	s_waitcnt lgkmcnt(0)
	v_mfma_f32_32x32x16_bf16 v[0:15], v[68:71], v[64:67], v[0:15]
	ds_read_b128 v[64:67], v100 offset:36928
	ds_read_b128 v[68:71], v160 offset:64
	ds_read_b128 v[72:75], v160 offset:8768
	ds_read_b128 v[80:83], v160 offset:17472
	ds_read_b128 v[84:87], v160 offset:26176
	ds_read_b128 v[76:79], v100 offset:36960
	s_waitcnt lgkmcnt(4)
	v_mfma_f32_32x32x16_bf16 v[48:63], v[68:71], v[64:67], v[48:63]
	ds_read_b128 v[68:71], v160 offset:96
	s_waitcnt lgkmcnt(4)
	v_mfma_f32_32x32x16_bf16 v[32:47], v[72:75], v[64:67], v[32:47]
	ds_read_b128 v[72:75], v160 offset:8800
	s_waitcnt lgkmcnt(4)
	v_mfma_f32_32x32x16_bf16 v[16:31], v[80:83], v[64:67], v[16:31]
	ds_read_b128 v[80:83], v160 offset:17504
	s_waitcnt lgkmcnt(4)
	v_mfma_f32_32x32x16_bf16 v[0:15], v[84:87], v[64:67], v[0:15]
	ds_read_b128 v[84:87], v160 offset:26208
	ds_read_b128 v[64:67], v100 offset:36992
	s_waitcnt lgkmcnt(4)
	v_mfma_f32_32x32x16_bf16 v[48:63], v[68:71], v[76:79], v[48:63]
	ds_read_b128 v[68:71], v160 offset:128
	s_waitcnt lgkmcnt(4)
	v_mfma_f32_32x32x16_bf16 v[32:47], v[72:75], v[76:79], v[32:47]
	ds_read_b128 v[72:75], v160 offset:8832
	s_waitcnt lgkmcnt(4)
	v_mfma_f32_32x32x16_bf16 v[16:31], v[80:83], v[76:79], v[16:31]
	ds_read_b128 v[80:83], v160 offset:17536
	s_waitcnt lgkmcnt(4)
	v_mfma_f32_32x32x16_bf16 v[0:15], v[84:87], v[76:79], v[0:15]
	ds_read_b128 v[84:87], v160 offset:26240
	ds_read_b128 v[76:79], v100 offset:37024
	s_waitcnt lgkmcnt(4)
	v_mfma_f32_32x32x16_bf16 v[48:63], v[68:71], v[64:67], v[48:63]
	ds_read_b128 v[68:71], v160 offset:160
	s_waitcnt lgkmcnt(4)
	v_mfma_f32_32x32x16_bf16 v[32:47], v[72:75], v[64:67], v[32:47]
	ds_read_b128 v[72:75], v160 offset:8864
	s_waitcnt lgkmcnt(4)
	v_mfma_f32_32x32x16_bf16 v[16:31], v[80:83], v[64:67], v[16:31]
	ds_read_b128 v[80:83], v160 offset:17568
	s_waitcnt lgkmcnt(4)
	v_mfma_f32_32x32x16_bf16 v[0:15], v[84:87], v[64:67], v[0:15]
	ds_read_b128 v[84:87], v160 offset:26272
	ds_read_b128 v[64:67], v100 offset:37056
	s_waitcnt lgkmcnt(4)
	v_mfma_f32_32x32x16_bf16 v[48:63], v[68:71], v[76:79], v[48:63]
	ds_read_b128 v[68:71], v160 offset:192
	s_waitcnt lgkmcnt(4)
	v_mfma_f32_32x32x16_bf16 v[32:47], v[72:75], v[76:79], v[32:47]
	ds_read_b128 v[72:75], v160 offset:8896
	s_waitcnt lgkmcnt(4)
	v_mfma_f32_32x32x16_bf16 v[16:31], v[80:83], v[76:79], v[16:31]
	ds_read_b128 v[80:83], v160 offset:17600
	s_waitcnt lgkmcnt(4)
	v_mfma_f32_32x32x16_bf16 v[0:15], v[84:87], v[76:79], v[0:15]
	ds_read_b128 v[84:87], v160 offset:26304
	ds_read_b128 v[76:79], v100 offset:37088
	s_waitcnt lgkmcnt(4)
	v_mfma_f32_32x32x16_bf16 v[48:63], v[68:71], v[64:67], v[48:63]
	ds_read_b128 v[68:71], v160 offset:224
	s_waitcnt lgkmcnt(4)
	v_mfma_f32_32x32x16_bf16 v[32:47], v[72:75], v[64:67], v[32:47]
	ds_read_b128 v[72:75], v160 offset:8928
	s_waitcnt lgkmcnt(4)
	v_mfma_f32_32x32x16_bf16 v[16:31], v[80:83], v[64:67], v[16:31]
	ds_read_b128 v[80:83], v160 offset:17632
	s_waitcnt lgkmcnt(4)
	v_mfma_f32_32x32x16_bf16 v[0:15], v[84:87], v[64:67], v[0:15]
	ds_read_b128 v[84:87], v160 offset:26336
	s_waitcnt lgkmcnt(3)
	v_mfma_f32_32x32x16_bf16 v[48:63], v[68:71], v[76:79], v[48:63]
	s_waitcnt lgkmcnt(2)
	v_mfma_f32_32x32x16_bf16 v[32:47], v[72:75], v[76:79], v[32:47]
	s_waitcnt lgkmcnt(1)
	v_mfma_f32_32x32x16_bf16 v[16:31], v[80:83], v[76:79], v[16:31]
	s_waitcnt lgkmcnt(0)
; DEV unsigned fkey(float v) { const unsigned u = __float_as_uint(v); return (u & 0x80000000u) ? ~u : (u | 0x80000000u); }
; __device__ void peer_q_topk_item(const Params& P, int l, int item, char* smem) {
;     ...
;       unsigned G1[16], G2[16], G3[16];
; #pragma unroll
;       for (int i = 0; i < 16; ++i) {
;         const int kb0 = (i & 3) + 8 * (i >> 2) + 4 * hk;
;         Lc[i] = (fkey(sa[0][i]) & ~0x7Fu) | (unsigned)(127 - kb0);
;         G1[i] = (fkey(sa[1][i]) & ~0x7Fu) | (unsigned)(127 - (32 + kb0));
;         G2[i] = (fkey(sa[2][i]) & ~0x7Fu) | (unsigned)(127 - (64 + kb0));
;         G3[i] = (fkey(sa[3][i]) & ~0x7Fu) | (unsigned)(127 - (96 + kb0));
;       }
	v_mfma_f32_32x32x16_bf16 v[0:15], v[84:87], v[76:79], v[0:15]
	s_nop 7
	s_mov_b32 vcc_lo, 0x80000000
	v_ashrrev_i32_e32 v64, 31, v48
	v_bitop3_b32 v48, v48, v64, vcc_lo bitop3:0x1e
	v_ashrrev_i32_e32 v64, 31, v32
	v_and_b32_e32 v48, 0xffffff80, v48
	v_bitop3_b32 v48, v48, s39, v159 bitop3:0x36
	v_bitop3_b32 v32, v32, v64, vcc_lo bitop3:0x1e
	v_ashrrev_i32_e32 v64, 31, v16
	v_and_b32_e32 v32, 0xffffff80, v32
	v_bitop3_b32 v32, v32, s38, v159 bitop3:0x36
	v_bitop3_b32 v16, v16, v64, vcc_lo bitop3:0x1e
	v_ashrrev_i32_e32 v64, 31, v0
	v_and_b32_e32 v16, 0xffffff80, v16
	v_bitop3_b32 v16, v16, 63, v159 bitop3:0x36
	v_bitop3_b32 v0, v0, v64, vcc_lo bitop3:0x1e
	v_ashrrev_i32_e32 v64, 31, v49
	v_and_b32_e32 v0, 0xffffff80, v0
	v_bitop3_b32 v0, v0, 31, v159 bitop3:0x36
	v_bitop3_b32 v49, v49, v64, vcc_lo bitop3:0x1e
	v_ashrrev_i32_e32 v64, 31, v33
	v_and_b32_e32 v49, 0xffffff80, v49
	v_bitop3_b32 v49, v49, s39, v163 bitop3:0x36
	v_bitop3_b32 v33, v33, v64, vcc_lo bitop3:0x1e
	v_ashrrev_i32_e32 v64, 31, v17
	v_and_b32_e32 v33, 0xffffff80, v33
	v_bitop3_b32 v33, v33, s38, v163 bitop3:0x36
	v_bitop3_b32 v17, v17, v64, vcc_lo bitop3:0x1e
	v_ashrrev_i32_e32 v64, 31, v1
	v_and_b32_e32 v17, 0xffffff80, v17
	v_bitop3_b32 v17, v17, 63, v163 bitop3:0x36
	v_bitop3_b32 v1, v1, v64, vcc_lo bitop3:0x1e
	v_ashrrev_i32_e32 v64, 31, v50
	v_and_b32_e32 v1, 0xffffff80, v1
	v_bitop3_b32 v1, v1, 31, v163 bitop3:0x36
	v_bitop3_b32 v50, v50, v64, vcc_lo bitop3:0x1e
	v_ashrrev_i32_e32 v64, 31, v34
	v_and_b32_e32 v50, 0xffffff80, v50
	v_bitop3_b32 v50, v50, s39, v164 bitop3:0x36
	v_bitop3_b32 v34, v34, v64, vcc_lo bitop3:0x1e
	v_ashrrev_i32_e32 v64, 31, v18
	v_and_b32_e32 v34, 0xffffff80, v34
	v_bitop3_b32 v34, v34, s38, v164 bitop3:0x36
	v_bitop3_b32 v18, v18, v64, vcc_lo bitop3:0x1e
	v_ashrrev_i32_e32 v64, 31, v2
	v_and_b32_e32 v18, 0xffffff80, v18
	v_bitop3_b32 v18, v18, 63, v164 bitop3:0x36
	v_bitop3_b32 v2, v2, v64, vcc_lo bitop3:0x1e
	v_ashrrev_i32_e32 v64, 31, v51
	v_and_b32_e32 v2, 0xffffff80, v2
	v_bitop3_b32 v2, v2, 31, v164 bitop3:0x36
	v_bitop3_b32 v51, v51, v64, vcc_lo bitop3:0x1e
	v_ashrrev_i32_e32 v64, 31, v35
	v_and_b32_e32 v51, 0xffffff80, v51
	v_bitop3_b32 v51, v51, s39, v166 bitop3:0x36
	v_bitop3_b32 v35, v35, v64, vcc_lo bitop3:0x1e
	v_ashrrev_i32_e32 v64, 31, v19
	v_and_b32_e32 v35, 0xffffff80, v35
	v_bitop3_b32 v35, v35, s38, v166 bitop3:0x36
	v_bitop3_b32 v19, v19, v64, vcc_lo bitop3:0x1e
	v_ashrrev_i32_e32 v64, 31, v3
	v_and_b32_e32 v19, 0xffffff80, v19
	v_bitop3_b32 v19, v19, 63, v166 bitop3:0x36
	v_bitop3_b32 v3, v3, v64, vcc_lo bitop3:0x1e
	v_ashrrev_i32_e32 v64, 31, v52
	v_and_b32_e32 v3, 0xffffff80, v3
	v_bitop3_b32 v3, v3, 31, v166 bitop3:0x36
	v_bitop3_b32 v52, v52, v64, vcc_lo bitop3:0x1e
	v_ashrrev_i32_e32 v64, 31, v36
	v_and_b32_e32 v52, 0xffffff80, v52
	v_bitop3_b32 v52, v52, s39, v167 bitop3:0x36
	v_bitop3_b32 v36, v36, v64, vcc_lo bitop3:0x1e
	v_ashrrev_i32_e32 v64, 31, v20
	v_and_b32_e32 v36, 0xffffff80, v36
	v_bitop3_b32 v36, v36, s38, v167 bitop3:0x36
	v_bitop3_b32 v20, v20, v64, vcc_lo bitop3:0x1e
	v_ashrrev_i32_e32 v64, 31, v4
	v_and_b32_e32 v20, 0xffffff80, v20
	v_bitop3_b32 v20, v20, 63, v167 bitop3:0x36
	v_bitop3_b32 v4, v4, v64, vcc_lo bitop3:0x1e
	v_ashrrev_i32_e32 v64, 31, v53
	v_and_b32_e32 v4, 0xffffff80, v4
	v_bitop3_b32 v4, v4, 31, v167 bitop3:0x36
	v_bitop3_b32 v53, v53, v64, vcc_lo bitop3:0x1e
	v_ashrrev_i32_e32 v64, 31, v37
	v_and_b32_e32 v53, 0xffffff80, v53
	v_bitop3_b32 v53, v53, s39, v171 bitop3:0x36
	v_bitop3_b32 v37, v37, v64, vcc_lo bitop3:0x1e
	v_ashrrev_i32_e32 v64, 31, v21
	v_and_b32_e32 v37, 0xffffff80, v37
	v_bitop3_b32 v37, v37, s38, v171 bitop3:0x36
	v_bitop3_b32 v21, v21, v64, vcc_lo bitop3:0x1e
	v_ashrrev_i32_e32 v64, 31, v5
	v_and_b32_e32 v21, 0xffffff80, v21
	v_bitop3_b32 v21, v21, 63, v171 bitop3:0x36
	v_bitop3_b32 v5, v5, v64, vcc_lo bitop3:0x1e
	v_ashrrev_i32_e32 v64, 31, v54
	v_and_b32_e32 v5, 0xffffff80, v5
	v_bitop3_b32 v5, v5, 31, v171 bitop3:0x36
	v_bitop3_b32 v54, v54, v64, vcc_lo bitop3:0x1e
	v_ashrrev_i32_e32 v64, 31, v38
	v_and_b32_e32 v54, 0xffffff80, v54
	v_bitop3_b32 v54, v54, s39, v172 bitop3:0x36
	v_bitop3_b32 v38, v38, v64, vcc_lo bitop3:0x1e
	v_ashrrev_i32_e32 v64, 31, v22
	v_and_b32_e32 v38, 0xffffff80, v38
	v_bitop3_b32 v38, v38, s38, v172 bitop3:0x36
	v_bitop3_b32 v22, v22, v64, vcc_lo bitop3:0x1e
	v_ashrrev_i32_e32 v64, 31, v6
	v_and_b32_e32 v22, 0xffffff80, v22
	v_bitop3_b32 v22, v22, 63, v172 bitop3:0x36
	v_bitop3_b32 v6, v6, v64, vcc_lo bitop3:0x1e
	v_ashrrev_i32_e32 v64, 31, v55
	v_and_b32_e32 v6, 0xffffff80, v6
	v_bitop3_b32 v6, v6, 31, v172 bitop3:0x36
	v_bitop3_b32 v55, v55, v64, vcc_lo bitop3:0x1e
	v_ashrrev_i32_e32 v64, 31, v39
	v_and_b32_e32 v55, 0xffffff80, v55
	v_bitop3_b32 v55, v55, s39, v173 bitop3:0x36
	v_bitop3_b32 v39, v39, v64, vcc_lo bitop3:0x1e
	v_ashrrev_i32_e32 v64, 31, v23
	v_and_b32_e32 v39, 0xffffff80, v39
	v_bitop3_b32 v39, v39, s38, v173 bitop3:0x36
	v_bitop3_b32 v23, v23, v64, vcc_lo bitop3:0x1e
	v_ashrrev_i32_e32 v64, 31, v7
	v_and_b32_e32 v23, 0xffffff80, v23
	v_bitop3_b32 v23, v23, 63, v173 bitop3:0x36
	v_bitop3_b32 v7, v7, v64, vcc_lo bitop3:0x1e
	v_ashrrev_i32_e32 v64, 31, v56
	v_and_b32_e32 v7, 0xffffff80, v7
	v_bitop3_b32 v7, v7, 31, v173 bitop3:0x36
	v_bitop3_b32 v56, v56, v64, vcc_lo bitop3:0x1e
	v_ashrrev_i32_e32 v64, 31, v40
	v_and_b32_e32 v56, 0xffffff80, v56
	v_bitop3_b32 v56, v56, s39, v169 bitop3:0x36
	v_bitop3_b32 v40, v40, v64, vcc_lo bitop3:0x1e
	v_ashrrev_i32_e32 v64, 31, v24
	v_and_b32_e32 v40, 0xffffff80, v40
	v_bitop3_b32 v40, v40, s38, v169 bitop3:0x36
	v_bitop3_b32 v24, v24, v64, vcc_lo bitop3:0x1e
	v_ashrrev_i32_e32 v64, 31, v8
; DEV unsigned fkey(float v) { const unsigned u = __float_as_uint(v); return (u & 0x80000000u) ? ~u : (u | 0x80000000u); }
; DEV void sort16_desc(unsigned (&x)[16]) {
; #pragma unroll
;   for (int k = 2; k <= 16; k <<= 1)
; #pragma unroll
;     for (int j = k >> 1; j > 0; j >>= 1)
; #pragma unroll
;       for (int i = 0; i < 16; ++i) {
;         const int p = i ^ j;
;         if (p > i) {
;           if ((i & k) == 0) { TK_CE(x[i], x[p]); } else { TK_CE(x[p], x[i]); }
;         }
;       }
; }
; __device__ void peer_q_topk_item(const Params& P, int l, int item, char* smem) {
;     ...
;       for (int i = 0; i < 16; ++i) {
;         const int kb0 = (i & 3) + 8 * (i >> 2) + 4 * hk;
;         Lc[i] = (fkey(sa[0][i]) & ~0x7Fu) | (unsigned)(127 - kb0);
;         G1[i] = (fkey(sa[1][i]) & ~0x7Fu) | (unsigned)(127 - (32 + kb0));
;         G2[i] = (fkey(sa[2][i]) & ~0x7Fu) | (unsigned)(127 - (64 + kb0));
;         G3[i] = (fkey(sa[3][i]) & ~0x7Fu) | (unsigned)(127 - (96 + kb0));
;       }
	v_and_b32_e32 v24, 0xffffff80, v24
	v_bitop3_b32 v24, v24, 63, v169 bitop3:0x36
	v_bitop3_b32 v8, v8, v64, vcc_lo bitop3:0x1e
	v_ashrrev_i32_e32 v64, 31, v57
	v_and_b32_e32 v8, 0xffffff80, v8
	v_bitop3_b32 v8, v8, 31, v169 bitop3:0x36
	v_bitop3_b32 v57, v57, v64, vcc_lo bitop3:0x1e
	v_ashrrev_i32_e32 v64, 31, v41
	v_and_b32_e32 v57, 0xffffff80, v57
	v_bitop3_b32 v57, v57, s39, v174 bitop3:0x36
	v_bitop3_b32 v41, v41, v64, vcc_lo bitop3:0x1e
	v_ashrrev_i32_e32 v64, 31, v25
	v_and_b32_e32 v41, 0xffffff80, v41
	v_bitop3_b32 v41, v41, s38, v174 bitop3:0x36
	v_bitop3_b32 v25, v25, v64, vcc_lo bitop3:0x1e
	v_ashrrev_i32_e32 v64, 31, v9
	v_and_b32_e32 v25, 0xffffff80, v25
	v_bitop3_b32 v25, v25, 63, v174 bitop3:0x36
	v_bitop3_b32 v9, v9, v64, vcc_lo bitop3:0x1e
	v_ashrrev_i32_e32 v64, 31, v58
	v_and_b32_e32 v9, 0xffffff80, v9
	v_bitop3_b32 v9, v9, 31, v174 bitop3:0x36
	v_bitop3_b32 v58, v58, v64, vcc_lo bitop3:0x1e
	v_ashrrev_i32_e32 v64, 31, v42
	v_and_b32_e32 v58, 0xffffff80, v58
	v_bitop3_b32 v58, v58, s39, v175 bitop3:0x36
	v_bitop3_b32 v42, v42, v64, vcc_lo bitop3:0x1e
	v_ashrrev_i32_e32 v64, 31, v26
	v_and_b32_e32 v42, 0xffffff80, v42
	v_bitop3_b32 v42, v42, s38, v175 bitop3:0x36
	v_bitop3_b32 v26, v26, v64, vcc_lo bitop3:0x1e
	v_ashrrev_i32_e32 v64, 31, v10
	v_and_b32_e32 v26, 0xffffff80, v26
	v_bitop3_b32 v26, v26, 63, v175 bitop3:0x36
	v_bitop3_b32 v10, v10, v64, vcc_lo bitop3:0x1e
	v_ashrrev_i32_e32 v64, 31, v59
	v_and_b32_e32 v10, 0xffffff80, v10
	v_bitop3_b32 v10, v10, 31, v175 bitop3:0x36
	v_bitop3_b32 v59, v59, v64, vcc_lo bitop3:0x1e
	v_ashrrev_i32_e32 v64, 31, v43
	v_and_b32_e32 v59, 0xffffff80, v59
	v_bitop3_b32 v59, v59, s39, v179 bitop3:0x36
	v_bitop3_b32 v43, v43, v64, vcc_lo bitop3:0x1e
	v_ashrrev_i32_e32 v64, 31, v27
	v_and_b32_e32 v43, 0xffffff80, v43
	v_bitop3_b32 v43, v43, s38, v179 bitop3:0x36
	v_bitop3_b32 v27, v27, v64, vcc_lo bitop3:0x1e
	v_ashrrev_i32_e32 v64, 31, v11
	v_and_b32_e32 v27, 0xffffff80, v27
	v_bitop3_b32 v27, v27, 63, v179 bitop3:0x36
	v_bitop3_b32 v11, v11, v64, vcc_lo bitop3:0x1e
	v_ashrrev_i32_e32 v64, 31, v60
	v_and_b32_e32 v11, 0xffffff80, v11
	v_bitop3_b32 v11, v11, 31, v179 bitop3:0x36
	v_bitop3_b32 v60, v60, v64, vcc_lo bitop3:0x1e
	v_ashrrev_i32_e32 v64, 31, v44
	v_and_b32_e32 v60, 0xffffff80, v60
	v_bitop3_b32 v60, v60, s39, v170 bitop3:0x36
	v_bitop3_b32 v44, v44, v64, vcc_lo bitop3:0x1e
	v_ashrrev_i32_e32 v64, 31, v28
	v_and_b32_e32 v44, 0xffffff80, v44
	v_bitop3_b32 v44, v44, s38, v170 bitop3:0x36
	v_bitop3_b32 v28, v28, v64, vcc_lo bitop3:0x1e
	v_ashrrev_i32_e32 v64, 31, v12
	v_and_b32_e32 v28, 0xffffff80, v28
	v_bitop3_b32 v28, v28, 63, v170 bitop3:0x36
	v_bitop3_b32 v12, v12, v64, vcc_lo bitop3:0x1e
	v_ashrrev_i32_e32 v64, 31, v61
	v_and_b32_e32 v12, 0xffffff80, v12
	v_bitop3_b32 v12, v12, 31, v170 bitop3:0x36
	v_bitop3_b32 v61, v61, v64, vcc_lo bitop3:0x1e
	v_ashrrev_i32_e32 v64, 31, v45
	v_and_b32_e32 v61, 0xffffff80, v61
	v_bitop3_b32 v61, v61, s39, v180 bitop3:0x36
	v_bitop3_b32 v45, v45, v64, vcc_lo bitop3:0x1e
	v_ashrrev_i32_e32 v64, 31, v29
	v_and_b32_e32 v45, 0xffffff80, v45
	v_bitop3_b32 v45, v45, s38, v180 bitop3:0x36
	v_bitop3_b32 v29, v29, v64, vcc_lo bitop3:0x1e
	v_ashrrev_i32_e32 v64, 31, v13
	v_and_b32_e32 v29, 0xffffff80, v29
	v_bitop3_b32 v29, v29, 63, v180 bitop3:0x36
	v_bitop3_b32 v13, v13, v64, vcc_lo bitop3:0x1e
	v_ashrrev_i32_e32 v64, 31, v62
	v_and_b32_e32 v13, 0xffffff80, v13
	v_bitop3_b32 v13, v13, 31, v180 bitop3:0x36
	v_bitop3_b32 v62, v62, v64, vcc_lo bitop3:0x1e
	v_ashrrev_i32_e32 v64, 31, v46
	v_and_b32_e32 v62, 0xffffff80, v62
	v_bitop3_b32 v62, v62, s39, v181 bitop3:0x36
	v_bitop3_b32 v46, v46, v64, vcc_lo bitop3:0x1e
	v_ashrrev_i32_e32 v64, 31, v30
	v_and_b32_e32 v46, 0xffffff80, v46
	v_bitop3_b32 v46, v46, s38, v181 bitop3:0x36
	v_bitop3_b32 v30, v30, v64, vcc_lo bitop3:0x1e
	v_ashrrev_i32_e32 v64, 31, v14
	v_and_b32_e32 v30, 0xffffff80, v30
	v_bitop3_b32 v30, v30, 63, v181 bitop3:0x36
	v_bitop3_b32 v14, v14, v64, vcc_lo bitop3:0x1e
	v_ashrrev_i32_e32 v64, 31, v63
	v_and_b32_e32 v14, 0xffffff80, v14
	v_bitop3_b32 v14, v14, 31, v181 bitop3:0x36
	v_bitop3_b32 v63, v63, v64, vcc_lo bitop3:0x1e
	v_ashrrev_i32_e32 v64, 31, v47
	v_and_b32_e32 v63, 0xffffff80, v63
	v_bitop3_b32 v63, v63, s39, v182 bitop3:0x36
	v_bitop3_b32 v47, v47, v64, vcc_lo bitop3:0x1e
	v_ashrrev_i32_e32 v64, 31, v31
	v_and_b32_e32 v47, 0xffffff80, v47
	v_bitop3_b32 v47, v47, s38, v182 bitop3:0x36
	v_bitop3_b32 v31, v31, v64, vcc_lo bitop3:0x1e
	v_ashrrev_i32_e32 v64, 31, v15
	v_and_b32_e32 v31, 0xffffff80, v31
	v_bitop3_b32 v31, v31, 63, v182 bitop3:0x36
	v_bitop3_b32 v15, v15, v64, vcc_lo bitop3:0x1e
	v_and_b32_e32 v15, 0xffffff80, v15
	v_bitop3_b32 v15, v15, 31, v182 bitop3:0x36
	v_max_u32_e32 v64, v48, v49
	v_min_u32_e32 v48, v48, v49
	v_max_u32_e32 v49, v51, v50
	v_min_u32_e32 v50, v51, v50
	v_max_u32_e32 v51, v52, v53
	v_min_u32_e32 v52, v52, v53
	v_max_u32_e32 v53, v55, v54
	v_min_u32_e32 v54, v55, v54
	v_max_u32_e32 v55, v56, v57
	v_min_u32_e32 v56, v56, v57
	v_max_u32_e32 v57, v59, v58
	v_min_u32_e32 v58, v59, v58
	v_max_u32_e32 v59, v60, v61
	v_min_u32_e32 v60, v60, v61
	v_max_u32_e32 v61, v63, v62
	v_min_u32_e32 v62, v63, v62
	v_max_u32_e32 v72, v32, v33
	v_min_u32_e32 v32, v32, v33
	v_max_u32_e32 v33, v35, v34
	v_min_u32_e32 v34, v35, v34
	v_max_u32_e32 v35, v36, v37
	v_min_u32_e32 v36, v36, v37
	v_max_u32_e32 v37, v39, v38
	v_min_u32_e32 v38, v39, v38
	v_max_u32_e32 v39, v40, v41
	v_min_u32_e32 v40, v40, v41
	v_max_u32_e32 v41, v43, v42
	v_min_u32_e32 v42, v43, v42
	v_max_u32_e32 v43, v44, v45
	v_min_u32_e32 v44, v44, v45
	v_max_u32_e32 v45, v47, v46
	v_min_u32_e32 v46, v47, v46
; DEV void sort16_desc(unsigned (&x)[16]) {
; #pragma unroll
;   for (int k = 2; k <= 16; k <<= 1)
; #pragma unroll
;     for (int j = k >> 1; j > 0; j >>= 1)
; #pragma unroll
;       for (int i = 0; i < 16; ++i) {
;         const int p = i ^ j;
;         if (p > i) {
;           if ((i & k) == 0) { TK_CE(x[i], x[p]); } else { TK_CE(x[p], x[i]); }
;         }
;       }
; }
	v_max_u32_e32 v80, v16, v17
	v_min_u32_e32 v16, v16, v17
	v_max_u32_e32 v17, v19, v18
	v_min_u32_e32 v18, v19, v18
	v_max_u32_e32 v19, v20, v21
	v_min_u32_e32 v20, v20, v21
	v_max_u32_e32 v21, v23, v22
	v_min_u32_e32 v22, v23, v22
	v_max_u32_e32 v23, v24, v25
	v_min_u32_e32 v24, v24, v25
	v_max_u32_e32 v25, v27, v26
	v_min_u32_e32 v26, v27, v26
	v_max_u32_e32 v27, v28, v29
	v_min_u32_e32 v28, v28, v29
	v_max_u32_e32 v29, v31, v30
	v_min_u32_e32 v30, v31, v30
	v_max_u32_e32 v88, v0, v1
	v_min_u32_e32 v0, v0, v1
	v_max_u32_e32 v1, v3, v2
	v_min_u32_e32 v2, v3, v2
	v_max_u32_e32 v3, v4, v5
	v_min_u32_e32 v4, v4, v5
	v_max_u32_e32 v5, v7, v6
	v_min_u32_e32 v6, v7, v6
	v_max_u32_e32 v7, v8, v9
	v_min_u32_e32 v8, v8, v9
	v_max_u32_e32 v9, v11, v10
	v_min_u32_e32 v10, v11, v10
	v_max_u32_e32 v11, v12, v13
	v_min_u32_e32 v12, v12, v13
	v_max_u32_e32 v13, v15, v14
	v_min_u32_e32 v14, v15, v14
	v_max_u32_e32 v63, v64, v50
	v_min_u32_e32 v50, v64, v50
	v_max_u32_e32 v64, v48, v49
	v_min_u32_e32 v48, v48, v49
	v_max_u32_e32 v49, v54, v51
	v_min_u32_e32 v51, v54, v51
	v_max_u32_e32 v54, v53, v52
	v_min_u32_e32 v52, v53, v52
	v_max_u32_e32 v53, v55, v58
	v_min_u32_e32 v55, v55, v58
	v_max_u32_e32 v58, v56, v57
	v_min_u32_e32 v56, v56, v57
	v_max_u32_e32 v57, v62, v59
	v_min_u32_e32 v59, v62, v59
	v_max_u32_e32 v62, v61, v60
	v_min_u32_e32 v60, v61, v60
	v_max_u32_e32 v47, v72, v34
	v_min_u32_e32 v34, v72, v34
	v_max_u32_e32 v72, v32, v33
	v_min_u32_e32 v32, v32, v33
	v_max_u32_e32 v33, v38, v35
	v_min_u32_e32 v35, v38, v35
	v_max_u32_e32 v38, v37, v36
	v_min_u32_e32 v36, v37, v36
	v_max_u32_e32 v37, v39, v42
	v_min_u32_e32 v39, v39, v42
	v_max_u32_e32 v42, v40, v41
	v_min_u32_e32 v40, v40, v41
	v_max_u32_e32 v41, v46, v43
	v_min_u32_e32 v43, v46, v43
	v_max_u32_e32 v46, v45, v44
	v_min_u32_e32 v44, v45, v44
	v_max_u32_e32 v31, v80, v18
	v_min_u32_e32 v18, v80, v18
	v_max_u32_e32 v80, v16, v17
	v_min_u32_e32 v16, v16, v17
	v_max_u32_e32 v17, v22, v19
	v_min_u32_e32 v19, v22, v19
	v_max_u32_e32 v22, v21, v20
	v_min_u32_e32 v20, v21, v20
	v_max_u32_e32 v21, v23, v26
	v_min_u32_e32 v23, v23, v26
	v_max_u32_e32 v26, v24, v25
	v_min_u32_e32 v24, v24, v25
	v_max_u32_e32 v25, v30, v27
	v_min_u32_e32 v27, v30, v27
	v_max_u32_e32 v30, v29, v28
	v_min_u32_e32 v28, v29, v28
	v_max_u32_e32 v15, v88, v2
	v_min_u32_e32 v2, v88, v2
	v_max_u32_e32 v88, v0, v1
	v_min_u32_e32 v0, v0, v1
	v_max_u32_e32 v1, v6, v3
	v_min_u32_e32 v3, v6, v3
	v_max_u32_e32 v6, v5, v4
	v_min_u32_e32 v4, v5, v4
	v_max_u32_e32 v5, v7, v10
	v_min_u32_e32 v7, v7, v10
	v_max_u32_e32 v10, v8, v9
	v_min_u32_e32 v8, v8, v9
	v_max_u32_e32 v9, v14, v11
	v_min_u32_e32 v11, v14, v11
	v_max_u32_e32 v14, v13, v12
	v_min_u32_e32 v12, v13, v12
	v_max_u32_e32 v61, v63, v64
	v_min_u32_e32 v63, v63, v64
	v_max_u32_e32 v64, v50, v48
	v_min_u32_e32 v48, v50, v48
	v_max_u32_e32 v50, v52, v51
	v_min_u32_e32 v51, v52, v51
	v_max_u32_e32 v52, v54, v49
	v_min_u32_e32 v49, v54, v49
	v_max_u32_e32 v54, v53, v58
	v_min_u32_e32 v53, v53, v58
	v_max_u32_e32 v58, v55, v56
	v_min_u32_e32 v55, v55, v56
	v_max_u32_e32 v56, v60, v59
	v_min_u32_e32 v59, v60, v59
	v_max_u32_e32 v60, v62, v57
	v_min_u32_e32 v57, v62, v57
	v_max_u32_e32 v45, v47, v72
	v_min_u32_e32 v47, v47, v72
	v_max_u32_e32 v72, v34, v32
	v_min_u32_e32 v32, v34, v32
	v_max_u32_e32 v34, v36, v35
	v_min_u32_e32 v35, v36, v35
	v_max_u32_e32 v36, v38, v33
	v_min_u32_e32 v33, v38, v33
	v_max_u32_e32 v38, v37, v42
	v_min_u32_e32 v37, v37, v42
	v_max_u32_e32 v42, v39, v40
	v_min_u32_e32 v39, v39, v40
	v_max_u32_e32 v40, v44, v43
	v_min_u32_e32 v43, v44, v43
	v_max_u32_e32 v44, v46, v41
	v_min_u32_e32 v41, v46, v41
	v_max_u32_e32 v29, v31, v80
	v_min_u32_e32 v31, v31, v80
	v_max_u32_e32 v80, v18, v16
	v_min_u32_e32 v16, v18, v16
	v_max_u32_e32 v18, v20, v19
	v_min_u32_e32 v19, v20, v19
	v_max_u32_e32 v20, v22, v17
	v_min_u32_e32 v17, v22, v17
	v_max_u32_e32 v22, v21, v26
	v_min_u32_e32 v21, v21, v26
	v_max_u32_e32 v26, v23, v24
	v_min_u32_e32 v23, v23, v24
	v_max_u32_e32 v24, v28, v27
	v_min_u32_e32 v27, v28, v27
	v_max_u32_e32 v28, v30, v25
	v_min_u32_e32 v25, v30, v25
	v_max_u32_e32 v13, v15, v88
	v_min_u32_e32 v15, v15, v88
	v_max_u32_e32 v88, v2, v0
	v_min_u32_e32 v0, v2, v0
	v_max_u32_e32 v2, v4, v3
	v_min_u32_e32 v3, v4, v3
	v_max_u32_e32 v4, v6, v1
	v_min_u32_e32 v1, v6, v1
	v_max_u32_e32 v6, v5, v10
	v_min_u32_e32 v5, v5, v10
	v_max_u32_e32 v10, v7, v8
	v_min_u32_e32 v7, v7, v8
	v_max_u32_e32 v8, v12, v11
	v_min_u32_e32 v11, v12, v11
	v_max_u32_e32 v12, v14, v9
	v_min_u32_e32 v9, v14, v9
	v_max_u32_e32 v62, v61, v51
	v_min_u32_e32 v51, v61, v51
	v_max_u32_e32 v61, v63, v50
	v_min_u32_e32 v50, v63, v50
	v_max_u32_e32 v63, v64, v49
	v_min_u32_e32 v49, v64, v49
	v_max_u32_e32 v64, v48, v52
	v_min_u32_e32 v48, v48, v52
	v_max_u32_e32 v52, v59, v54
	v_min_u32_e32 v54, v59, v54
	v_max_u32_e32 v59, v56, v53
	v_min_u32_e32 v53, v56, v53
	v_max_u32_e32 v56, v57, v58
	v_min_u32_e32 v57, v57, v58
	v_max_u32_e32 v58, v60, v55
	v_min_u32_e32 v55, v60, v55
	v_max_u32_e32 v46, v45, v35
	v_min_u32_e32 v35, v45, v35
	v_max_u32_e32 v45, v47, v34
	v_min_u32_e32 v34, v47, v34
	v_max_u32_e32 v47, v72, v33
	v_min_u32_e32 v33, v72, v33
	v_max_u32_e32 v72, v32, v36
	v_min_u32_e32 v32, v32, v36
	v_max_u32_e32 v36, v43, v38
	v_min_u32_e32 v38, v43, v38
	v_max_u32_e32 v43, v40, v37
	v_min_u32_e32 v37, v40, v37
	v_max_u32_e32 v40, v41, v42
	v_min_u32_e32 v41, v41, v42
	v_max_u32_e32 v42, v44, v39
	v_min_u32_e32 v39, v44, v39
	v_max_u32_e32 v30, v29, v19
	v_min_u32_e32 v19, v29, v19
	v_max_u32_e32 v29, v31, v18
	v_min_u32_e32 v18, v31, v18
	v_max_u32_e32 v31, v80, v17
	v_min_u32_e32 v17, v80, v17
; DEV void sort16_desc(unsigned (&x)[16]) {
; #pragma unroll
;   for (int k = 2; k <= 16; k <<= 1)
; #pragma unroll
;     for (int j = k >> 1; j > 0; j >>= 1)
; #pragma unroll
;       for (int i = 0; i < 16; ++i) {
;         const int p = i ^ j;
;         if (p > i) {
;           if ((i & k) == 0) { TK_CE(x[i], x[p]); } else { TK_CE(x[p], x[i]); }
;         }
;       }
; }
	v_max_u32_e32 v80, v16, v20
	v_min_u32_e32 v16, v16, v20
	v_max_u32_e32 v20, v27, v22
	v_min_u32_e32 v22, v27, v22
	v_max_u32_e32 v27, v24, v21
	v_min_u32_e32 v21, v24, v21
	v_max_u32_e32 v24, v25, v26
	v_min_u32_e32 v25, v25, v26
	v_max_u32_e32 v26, v28, v23
	v_min_u32_e32 v23, v28, v23
	v_max_u32_e32 v14, v13, v3
	v_min_u32_e32 v3, v13, v3
	v_max_u32_e32 v13, v15, v2
	v_min_u32_e32 v2, v15, v2
	v_max_u32_e32 v15, v88, v1
	v_min_u32_e32 v1, v88, v1
	v_max_u32_e32 v88, v0, v4
	v_min_u32_e32 v0, v0, v4
	v_max_u32_e32 v4, v11, v6
	v_min_u32_e32 v6, v11, v6
	v_max_u32_e32 v11, v8, v5
	v_min_u32_e32 v5, v8, v5
	v_max_u32_e32 v8, v9, v10
	v_min_u32_e32 v9, v9, v10
	v_max_u32_e32 v10, v12, v7
	v_min_u32_e32 v7, v12, v7
	v_max_u32_e32 v60, v62, v63
	v_min_u32_e32 v62, v62, v63
	v_max_u32_e32 v63, v61, v64
	v_min_u32_e32 v61, v61, v64
	v_max_u32_e32 v64, v51, v49
	v_min_u32_e32 v49, v51, v49
	v_max_u32_e32 v51, v50, v48
	v_min_u32_e32 v48, v50, v48
	v_max_u32_e32 v50, v57, v54
	v_min_u32_e32 v54, v57, v54
	v_max_u32_e32 v57, v55, v53
	v_min_u32_e32 v53, v55, v53
	v_max_u32_e32 v55, v56, v52
	v_min_u32_e32 v52, v56, v52
	v_max_u32_e32 v56, v58, v59
	v_min_u32_e32 v58, v58, v59
	v_max_u32_e32 v44, v46, v47
	v_min_u32_e32 v46, v46, v47
	v_max_u32_e32 v47, v45, v72
	v_min_u32_e32 v45, v45, v72
	v_max_u32_e32 v72, v35, v33
	v_min_u32_e32 v33, v35, v33
	v_max_u32_e32 v35, v34, v32
	v_min_u32_e32 v32, v34, v32
	v_max_u32_e32 v34, v41, v38
	v_min_u32_e32 v38, v41, v38
	v_max_u32_e32 v41, v39, v37
	v_min_u32_e32 v37, v39, v37
	v_max_u32_e32 v39, v40, v36
	v_min_u32_e32 v36, v40, v36
	v_max_u32_e32 v40, v42, v43
	v_min_u32_e32 v42, v42, v43
	v_max_u32_e32 v28, v30, v31
	v_min_u32_e32 v30, v30, v31
	v_max_u32_e32 v31, v29, v80
	v_min_u32_e32 v29, v29, v80
	v_max_u32_e32 v80, v19, v17
	v_min_u32_e32 v17, v19, v17
	v_max_u32_e32 v19, v18, v16
	v_min_u32_e32 v16, v18, v16
	v_max_u32_e32 v18, v25, v22
	v_min_u32_e32 v22, v25, v22
	v_max_u32_e32 v25, v23, v21
	v_min_u32_e32 v21, v23, v21
	v_max_u32_e32 v23, v24, v20
	v_min_u32_e32 v20, v24, v20
	v_max_u32_e32 v24, v26, v27
	v_min_u32_e32 v26, v26, v27
	v_max_u32_e32 v12, v14, v15
	v_min_u32_e32 v14, v14, v15
	v_max_u32_e32 v15, v13, v88
	v_min_u32_e32 v13, v13, v88
	v_max_u32_e32 v88, v3, v1
	v_min_u32_e32 v1, v3, v1
	v_max_u32_e32 v3, v2, v0
	v_min_u32_e32 v0, v2, v0
	v_max_u32_e32 v2, v9, v6
	v_min_u32_e32 v6, v9, v6
	v_max_u32_e32 v9, v7, v5
	v_min_u32_e32 v5, v7, v5
	v_max_u32_e32 v7, v8, v4
	v_min_u32_e32 v4, v8, v4
	v_max_u32_e32 v8, v10, v11
	v_min_u32_e32 v10, v10, v11
	v_max_u32_e32 v59, v60, v63
	v_min_u32_e32 v60, v60, v63
	v_max_u32_e32 v63, v62, v61
	v_min_u32_e32 v61, v62, v61
	v_max_u32_e32 v62, v64, v51
	v_min_u32_e32 v51, v64, v51
	v_max_u32_e32 v64, v49, v48
	v_min_u32_e32 v48, v49, v48
	v_max_u32_e32 v49, v53, v54
	v_min_u32_e32 v53, v53, v54
	v_max_u32_e32 v54, v57, v50
	v_min_u32_e32 v50, v57, v50
	v_max_u32_e32 v57, v58, v52
	v_min_u32_e32 v52, v58, v52
	v_max_u32_e32 v58, v56, v55
	v_min_u32_e32 v55, v56, v55
	v_max_u32_e32 v43, v44, v47
	v_min_u32_e32 v44, v44, v47
	v_max_u32_e32 v47, v46, v45
	v_min_u32_e32 v45, v46, v45
	v_max_u32_e32 v46, v72, v35
	v_min_u32_e32 v35, v72, v35
	v_max_u32_e32 v72, v33, v32
	v_min_u32_e32 v32, v33, v32
	v_max_u32_e32 v33, v37, v38
	v_min_u32_e32 v37, v37, v38
	v_max_u32_e32 v38, v41, v34
	v_min_u32_e32 v34, v41, v34
	v_max_u32_e32 v41, v42, v36
	v_min_u32_e32 v36, v42, v36
	v_max_u32_e32 v42, v40, v39
	v_min_u32_e32 v39, v40, v39
	v_max_u32_e32 v27, v28, v31
	v_min_u32_e32 v28, v28, v31
	v_max_u32_e32 v31, v30, v29
	v_min_u32_e32 v29, v30, v29
	v_max_u32_e32 v30, v80, v19
	v_min_u32_e32 v19, v80, v19
	v_max_u32_e32 v80, v17, v16
	v_min_u32_e32 v16, v17, v16
	v_max_u32_e32 v17, v21, v22
	v_min_u32_e32 v21, v21, v22
	v_max_u32_e32 v22, v25, v18
	v_min_u32_e32 v18, v25, v18
	v_max_u32_e32 v25, v26, v20
	v_min_u32_e32 v20, v26, v20
	v_max_u32_e32 v26, v24, v23
	v_min_u32_e32 v23, v24, v23
	v_max_u32_e32 v11, v12, v15
	v_min_u32_e32 v12, v12, v15
	v_max_u32_e32 v15, v14, v13
	v_min_u32_e32 v13, v14, v13
	v_max_u32_e32 v14, v88, v3
	v_min_u32_e32 v3, v88, v3
	v_max_u32_e32 v88, v1, v0
	v_min_u32_e32 v0, v1, v0
	v_max_u32_e32 v1, v5, v6
	v_min_u32_e32 v5, v5, v6
	v_max_u32_e32 v6, v9, v2
	v_min_u32_e32 v2, v9, v2
	v_max_u32_e32 v9, v10, v4
	v_min_u32_e32 v4, v10, v4
	v_max_u32_e32 v10, v8, v7
	v_min_u32_e32 v7, v8, v7
	v_max_u32_e32 v56, v59, v53
	v_min_u32_e32 v53, v59, v53
	v_max_u32_e32 v59, v60, v49
	v_min_u32_e32 v49, v60, v49
	v_max_u32_e32 v60, v63, v50
	v_min_u32_e32 v50, v63, v50
	v_max_u32_e32 v63, v61, v54
	v_min_u32_e32 v54, v61, v54
	v_max_u32_e32 v61, v62, v52
	v_min_u32_e32 v52, v62, v52
	v_max_u32_e32 v62, v51, v57
	v_min_u32_e32 v51, v51, v57
	v_max_u32_e32 v57, v64, v55
	v_min_u32_e32 v55, v64, v55
	v_max_u32_e32 v64, v48, v58
	v_min_u32_e32 v48, v48, v58
	v_max_u32_e32 v40, v43, v37
	v_min_u32_e32 v37, v43, v37
	v_max_u32_e32 v43, v44, v33
	v_min_u32_e32 v33, v44, v33
	v_max_u32_e32 v44, v47, v34
	v_min_u32_e32 v34, v47, v34
	v_max_u32_e32 v47, v45, v38
	v_min_u32_e32 v38, v45, v38
	v_max_u32_e32 v45, v46, v36
	v_min_u32_e32 v36, v46, v36
	v_max_u32_e32 v46, v35, v41
	v_min_u32_e32 v35, v35, v41
	v_max_u32_e32 v41, v72, v39
	v_min_u32_e32 v39, v72, v39
	v_max_u32_e32 v72, v32, v42
	v_min_u32_e32 v32, v32, v42
	v_max_u32_e32 v24, v27, v21
	v_min_u32_e32 v21, v27, v21
	v_max_u32_e32 v27, v28, v17
	v_min_u32_e32 v17, v28, v17
	v_max_u32_e32 v28, v31, v18
	v_min_u32_e32 v18, v31, v18
	v_max_u32_e32 v31, v29, v22
	v_min_u32_e32 v22, v29, v22
	v_max_u32_e32 v29, v30, v20
	v_min_u32_e32 v20, v30, v20
	v_max_u32_e32 v30, v19, v25
	v_min_u32_e32 v19, v19, v25
; DEV void sort16_desc(unsigned (&x)[16]) {
; #pragma unroll
;   for (int k = 2; k <= 16; k <<= 1)
; #pragma unroll
;     for (int j = k >> 1; j > 0; j >>= 1)
; #pragma unroll
;       for (int i = 0; i < 16; ++i) {
;         const int p = i ^ j;
;         if (p > i) {
;           if ((i & k) == 0) { TK_CE(x[i], x[p]); } else { TK_CE(x[p], x[i]); }
;         }
;       }
; }
; DEV void merge_top16(unsigned (&x)[16], const unsigned (&y)[16]) {
; #pragma unroll
;   for (int i = 0; i < 16; ++i) x[i] = max(x[i], y[15 - i]);
; #pragma unroll
;   for (int j = 8; j > 0; j >>= 1)
; #pragma unroll
;     for (int i = 0; i < 16; ++i) {
;       const int p = i ^ j;
;       if (p > i) { TK_CE(x[i], x[p]); }
;     }
; }
; __device__ void peer_q_topk_item(const Params& P, int l, int item, char* smem) {
;     ...
;       sort16_desc(Lc); sort16_desc(G1); sort16_desc(G2); sort16_desc(G3);
;       merge_top16(Lc, G1); merge_top16(G2, G3); merge_top16(Lc, G2);
	v_max_u32_e32 v25, v80, v23
	v_min_u32_e32 v23, v80, v23
	v_max_u32_e32 v80, v16, v26
	v_min_u32_e32 v16, v16, v26
	v_max_u32_e32 v8, v11, v5
	v_min_u32_e32 v5, v11, v5
	v_max_u32_e32 v11, v12, v1
	v_min_u32_e32 v1, v12, v1
	v_max_u32_e32 v12, v15, v2
	v_min_u32_e32 v2, v15, v2
	v_max_u32_e32 v15, v13, v6
	v_min_u32_e32 v6, v13, v6
	v_max_u32_e32 v13, v14, v4
	v_min_u32_e32 v4, v14, v4
	v_max_u32_e32 v14, v3, v9
	v_min_u32_e32 v3, v3, v9
	v_max_u32_e32 v9, v88, v7
	v_min_u32_e32 v7, v88, v7
	v_max_u32_e32 v88, v0, v10
	v_min_u32_e32 v0, v0, v10
	v_max_u32_e32 v58, v56, v61
	v_min_u32_e32 v56, v56, v61
	v_max_u32_e32 v61, v59, v62
	v_min_u32_e32 v59, v59, v62
	v_max_u32_e32 v62, v60, v57
	v_min_u32_e32 v57, v60, v57
	v_max_u32_e32 v60, v63, v64
	v_min_u32_e32 v63, v63, v64
	v_max_u32_e32 v64, v53, v52
	v_min_u32_e32 v52, v53, v52
	v_max_u32_e32 v53, v49, v51
	v_min_u32_e32 v49, v49, v51
	v_max_u32_e32 v51, v50, v55
	v_min_u32_e32 v50, v50, v55
	v_max_u32_e32 v55, v54, v48
	v_min_u32_e32 v48, v54, v48
	v_max_u32_e32 v42, v40, v45
	v_min_u32_e32 v40, v40, v45
	v_max_u32_e32 v45, v43, v46
	v_min_u32_e32 v43, v43, v46
	v_max_u32_e32 v46, v44, v41
	v_min_u32_e32 v41, v44, v41
	v_max_u32_e32 v44, v47, v72
	v_min_u32_e32 v47, v47, v72
	v_max_u32_e32 v72, v37, v36
	v_min_u32_e32 v36, v37, v36
	v_max_u32_e32 v37, v33, v35
	v_min_u32_e32 v33, v33, v35
	v_max_u32_e32 v35, v34, v39
	v_min_u32_e32 v34, v34, v39
	v_max_u32_e32 v39, v38, v32
	v_min_u32_e32 v32, v38, v32
	v_max_u32_e32 v26, v24, v29
	v_min_u32_e32 v24, v24, v29
	v_max_u32_e32 v29, v27, v30
	v_min_u32_e32 v27, v27, v30
	v_max_u32_e32 v30, v28, v25
	v_min_u32_e32 v25, v28, v25
	v_max_u32_e32 v28, v31, v80
	v_min_u32_e32 v31, v31, v80
	v_max_u32_e32 v80, v21, v20
	v_min_u32_e32 v20, v21, v20
	v_max_u32_e32 v21, v17, v19
	v_min_u32_e32 v17, v17, v19
	v_max_u32_e32 v19, v18, v23
	v_min_u32_e32 v18, v18, v23
	v_max_u32_e32 v23, v22, v16
	v_min_u32_e32 v16, v22, v16
	v_max_u32_e32 v10, v8, v13
	v_min_u32_e32 v8, v8, v13
	v_max_u32_e32 v13, v11, v14
	v_min_u32_e32 v11, v11, v14
	v_max_u32_e32 v14, v12, v9
	v_min_u32_e32 v9, v12, v9
	v_max_u32_e32 v12, v15, v88
	v_min_u32_e32 v15, v15, v88
	v_max_u32_e32 v88, v5, v4
	v_min_u32_e32 v4, v5, v4
	v_max_u32_e32 v5, v1, v3
	v_min_u32_e32 v1, v1, v3
	v_max_u32_e32 v3, v2, v7
	v_min_u32_e32 v2, v2, v7
	v_max_u32_e32 v7, v6, v0
	v_min_u32_e32 v0, v6, v0
	v_max_u32_e32 v54, v58, v62
	v_min_u32_e32 v58, v58, v62
	v_max_u32_e32 v62, v61, v60
	v_min_u32_e32 v60, v61, v60
	v_max_u32_e32 v61, v56, v57
	v_min_u32_e32 v56, v56, v57
	v_max_u32_e32 v57, v59, v63
	v_min_u32_e32 v59, v59, v63
	v_max_u32_e32 v63, v64, v51
	v_min_u32_e32 v51, v64, v51
	v_max_u32_e32 v64, v53, v55
	v_min_u32_e32 v53, v53, v55
	v_max_u32_e32 v55, v52, v50
	v_min_u32_e32 v50, v52, v50
	v_max_u32_e32 v52, v49, v48
	v_min_u32_e32 v48, v49, v48
	v_max_u32_e32 v38, v42, v46
	v_min_u32_e32 v42, v42, v46
	v_max_u32_e32 v46, v45, v44
	v_min_u32_e32 v44, v45, v44
	v_max_u32_e32 v45, v40, v41
	v_min_u32_e32 v40, v40, v41
	v_max_u32_e32 v41, v43, v47
	v_min_u32_e32 v43, v43, v47
	v_max_u32_e32 v47, v72, v35
	v_min_u32_e32 v35, v72, v35
	v_max_u32_e32 v72, v37, v39
	v_min_u32_e32 v37, v37, v39
	v_max_u32_e32 v39, v36, v34
	v_min_u32_e32 v34, v36, v34
	v_max_u32_e32 v36, v33, v32
	v_min_u32_e32 v32, v33, v32
	v_max_u32_e32 v22, v26, v30
	v_min_u32_e32 v26, v26, v30
	v_max_u32_e32 v30, v29, v28
	v_min_u32_e32 v28, v29, v28
	v_max_u32_e32 v29, v24, v25
	v_min_u32_e32 v24, v24, v25
	v_max_u32_e32 v25, v27, v31
	v_min_u32_e32 v27, v27, v31
	v_max_u32_e32 v31, v80, v19
	v_min_u32_e32 v19, v80, v19
	v_max_u32_e32 v80, v21, v23
	v_min_u32_e32 v21, v21, v23
	v_max_u32_e32 v23, v20, v18
	v_min_u32_e32 v18, v20, v18
	v_max_u32_e32 v20, v17, v16
	v_min_u32_e32 v16, v17, v16
	v_max_u32_e32 v6, v10, v14
	v_min_u32_e32 v10, v10, v14
	v_max_u32_e32 v14, v13, v12
	v_min_u32_e32 v12, v13, v12
	v_max_u32_e32 v13, v8, v9
	v_min_u32_e32 v8, v8, v9
	v_max_u32_e32 v9, v11, v15
	v_min_u32_e32 v11, v11, v15
	v_max_u32_e32 v15, v88, v3
	v_min_u32_e32 v3, v88, v3
	v_max_u32_e32 v88, v5, v7
	v_min_u32_e32 v5, v5, v7
	v_max_u32_e32 v7, v4, v2
	v_min_u32_e32 v2, v4, v2
	v_max_u32_e32 v4, v1, v0
	v_min_u32_e32 v0, v1, v0
	v_min_u32_e32 v49, v54, v62
	v_min_u32_e32 v65, v58, v60
	v_min_u32_e32 v66, v61, v57
	v_min_u32_e32 v67, v56, v59
	v_min_u32_e32 v68, v63, v64
	v_min_u32_e32 v69, v51, v53
	v_min_u32_e32 v70, v55, v52
	v_min_u32_e32 v71, v50, v48
	v_min_u32_e32 v33, v38, v46
	v_min_u32_e32 v73, v42, v44
	v_min_u32_e32 v74, v45, v41
	v_min_u32_e32 v75, v40, v43
	v_min_u32_e32 v76, v47, v72
	v_min_u32_e32 v77, v35, v37
	v_min_u32_e32 v78, v39, v36
	v_min_u32_e32 v79, v34, v32
	v_min_u32_e32 v17, v22, v30
	v_min_u32_e32 v81, v26, v28
	v_min_u32_e32 v82, v29, v25
	v_min_u32_e32 v83, v24, v27
	v_min_u32_e32 v84, v31, v80
	v_min_u32_e32 v85, v19, v21
	v_min_u32_e32 v86, v23, v20
	v_min_u32_e32 v87, v18, v16
	v_min_u32_e32 v1, v6, v14
	v_min_u32_e32 v89, v10, v12
	v_min_u32_e32 v90, v13, v9
	v_min_u32_e32 v91, v8, v11
	v_min_u32_e32 v92, v15, v88
	v_min_u32_e32 v93, v3, v5
	v_min_u32_e32 v94, v7, v4
	v_min_u32_e32 v95, v2, v0
	v_max3_u32 v54, v54, v62, v79
	v_max3_u32 v32, v49, v34, v32
	v_max3_u32 v34, v58, v60, v78
	v_max3_u32 v36, v65, v39, v36
	v_max3_u32 v39, v61, v57, v77
	v_max3_u32 v35, v66, v35, v37
	v_max3_u32 v37, v56, v59, v76
	v_max3_u32 v47, v67, v47, v72
	v_max3_u32 v49, v63, v64, v75
	v_max3_u32 v40, v68, v40, v43
	v_max3_u32 v43, v51, v53, v74
	v_max3_u32 v41, v69, v45, v41
	v_max3_u32 v45, v55, v52, v73
	v_max3_u32 v42, v70, v42, v44
	v_max3_u32 v33, v50, v48, v33
	v_max3_u32 v38, v71, v38, v46
	v_max3_u32 v22, v22, v30, v95
; DEV unsigned xor32_u(unsigned v) { return (unsigned)__shfl_xor((int)v, 32, 64); }
; DEV void merge_top16(unsigned (&x)[16], const unsigned (&y)[16]) {
; #pragma unroll
;   for (int i = 0; i < 16; ++i) x[i] = max(x[i], y[15 - i]);
; #pragma unroll
;   for (int j = 8; j > 0; j >>= 1)
; #pragma unroll
;     for (int i = 0; i < 16; ++i) {
;       const int p = i ^ j;
;       if (p > i) { TK_CE(x[i], x[p]); }
;     }
; }
; __device__ void peer_q_topk_item(const Params& P, int l, int item, char* smem) {
;     ...
;       sort16_desc(Lc); sort16_desc(G1); sort16_desc(G2); sort16_desc(G3);
;       merge_top16(Lc, G1); merge_top16(G2, G3); merge_top16(Lc, G2);
;     }
;     {
;       unsigned oth[16];
; #pragma unroll
;       for (int i = 0; i < 16; ++i) oth[i] = xor32_u(Lc[i]);
;       merge_top16(Lc, oth);
	v_max3_u32 v0, v17, v2, v0
	v_max3_u32 v2, v26, v28, v94
	v_max3_u32 v4, v81, v7, v4
	v_max3_u32 v7, v29, v25, v93
	v_max3_u32 v3, v82, v3, v5
	v_max3_u32 v5, v24, v27, v92
	v_max3_u32 v15, v83, v15, v88
	v_max3_u32 v17, v31, v80, v91
	v_max3_u32 v8, v84, v8, v11
	v_max3_u32 v11, v19, v21, v90
	v_max3_u32 v9, v85, v13, v9
	v_max3_u32 v13, v23, v20, v89
	v_max3_u32 v10, v86, v10, v12
	v_max3_u32 v1, v18, v16, v1
	v_max3_u32 v6, v87, v6, v14
	v_max_u32_e32 v44, v54, v49
	v_min_u32_e32 v46, v54, v49
	v_max_u32_e32 v48, v32, v40
	v_min_u32_e32 v32, v32, v40
	v_max_u32_e32 v40, v34, v43
	v_min_u32_e32 v34, v34, v43
	v_max_u32_e32 v43, v36, v41
	v_min_u32_e32 v36, v36, v41
	v_max_u32_e32 v41, v39, v45
	v_min_u32_e32 v39, v39, v45
	v_max_u32_e32 v45, v35, v42
	v_min_u32_e32 v35, v35, v42
	v_max_u32_e32 v42, v37, v33
	v_min_u32_e32 v33, v37, v33
	v_max_u32_e32 v37, v47, v38
	v_min_u32_e32 v38, v47, v38
	v_max_u32_e32 v12, v22, v17
	v_min_u32_e32 v14, v22, v17
	v_max_u32_e32 v16, v0, v8
	v_min_u32_e32 v0, v0, v8
	v_max_u32_e32 v8, v2, v11
	v_min_u32_e32 v2, v2, v11
	v_max_u32_e32 v11, v4, v9
	v_min_u32_e32 v4, v4, v9
	v_max_u32_e32 v9, v7, v13
	v_min_u32_e32 v7, v7, v13
	v_max_u32_e32 v13, v3, v10
	v_min_u32_e32 v3, v3, v10
	v_max_u32_e32 v10, v5, v1
	v_min_u32_e32 v1, v5, v1
	v_max_u32_e32 v5, v15, v6
	v_min_u32_e32 v6, v15, v6
	v_max_u32_e32 v47, v44, v41
	v_min_u32_e32 v41, v44, v41
	v_max_u32_e32 v44, v48, v45
	v_min_u32_e32 v45, v48, v45
	v_max_u32_e32 v48, v40, v42
	v_min_u32_e32 v40, v40, v42
	v_max_u32_e32 v42, v43, v37
	v_min_u32_e32 v37, v43, v37
	v_max_u32_e32 v43, v46, v39
	v_min_u32_e32 v39, v46, v39
	v_max_u32_e32 v46, v32, v35
	v_min_u32_e32 v32, v32, v35
	v_max_u32_e32 v35, v34, v33
	v_min_u32_e32 v33, v34, v33
	v_max_u32_e32 v34, v36, v38
	v_min_u32_e32 v36, v36, v38
	v_max_u32_e32 v15, v12, v9
	v_min_u32_e32 v9, v12, v9
	v_max_u32_e32 v12, v16, v13
	v_min_u32_e32 v13, v16, v13
	v_max_u32_e32 v16, v8, v10
	v_min_u32_e32 v8, v8, v10
	v_max_u32_e32 v10, v11, v5
	v_min_u32_e32 v5, v11, v5
	v_max_u32_e32 v11, v14, v7
	v_min_u32_e32 v7, v14, v7
	v_max_u32_e32 v14, v0, v3
	v_min_u32_e32 v0, v0, v3
	v_max_u32_e32 v3, v2, v1
	v_min_u32_e32 v1, v2, v1
	v_max_u32_e32 v2, v4, v6
	v_min_u32_e32 v4, v4, v6
	v_max_u32_e32 v38, v47, v48
	v_min_u32_e32 v47, v47, v48
	v_max_u32_e32 v48, v44, v42
	v_min_u32_e32 v42, v44, v42
	v_max_u32_e32 v44, v41, v40
	v_min_u32_e32 v40, v41, v40
	v_max_u32_e32 v41, v45, v37
	v_min_u32_e32 v37, v45, v37
	v_max_u32_e32 v45, v43, v35
	v_min_u32_e32 v35, v43, v35
	v_max_u32_e32 v43, v46, v34
	v_min_u32_e32 v34, v46, v34
	v_max_u32_e32 v46, v39, v33
	v_min_u32_e32 v33, v39, v33
	v_max_u32_e32 v39, v32, v36
	v_min_u32_e32 v32, v32, v36
	v_max_u32_e32 v6, v15, v16
	v_min_u32_e32 v15, v15, v16
	v_max_u32_e32 v16, v12, v10
	v_min_u32_e32 v10, v12, v10
	v_max_u32_e32 v12, v9, v8
	v_min_u32_e32 v8, v9, v8
	v_max_u32_e32 v9, v13, v5
	v_min_u32_e32 v5, v13, v5
	v_max_u32_e32 v13, v11, v3
	v_min_u32_e32 v3, v11, v3
	v_max_u32_e32 v11, v14, v2
	v_min_u32_e32 v2, v14, v2
	v_max_u32_e32 v14, v7, v1
	v_min_u32_e32 v1, v7, v1
	v_max_u32_e32 v7, v0, v4
	v_min_u32_e32 v0, v0, v4
	v_min_u32_e32 v36, v38, v48
	v_min_u32_e32 v49, v47, v42
	v_min_u32_e32 v50, v44, v41
	v_min_u32_e32 v51, v40, v37
	v_min_u32_e32 v52, v45, v43
	v_min_u32_e32 v53, v35, v34
	v_min_u32_e32 v54, v46, v39
	v_min_u32_e32 v55, v33, v32
	v_min_u32_e32 v4, v6, v16
	v_min_u32_e32 v17, v15, v10
	v_min_u32_e32 v18, v12, v9
	v_min_u32_e32 v19, v8, v5
	v_min_u32_e32 v20, v13, v11
	v_min_u32_e32 v21, v3, v2
	v_min_u32_e32 v22, v14, v7
	v_min_u32_e32 v23, v1, v0
	v_max3_u32 v23, v38, v48, v23
	v_max3_u32 v0, v36, v1, v0
	v_max3_u32 v1, v47, v42, v22
	v_max3_u32 v7, v49, v14, v7
	v_max3_u32 v14, v44, v41, v21
	v_max3_u32 v2, v50, v3, v2
	v_max3_u32 v3, v40, v37, v20
	v_max3_u32 v11, v51, v13, v11
	v_max3_u32 v13, v45, v43, v19
	v_max3_u32 v5, v52, v8, v5
	v_max3_u32 v8, v35, v34, v18
	v_max3_u32 v9, v53, v12, v9
	v_max3_u32 v12, v46, v39, v17
	v_max3_u32 v10, v54, v15, v10
	v_max3_u32 v4, v33, v32, v4
	v_max3_u32 v6, v55, v6, v16
	v_max_u32_e32 v15, v23, v13
	v_min_u32_e32 v13, v23, v13
	v_max_u32_e32 v16, v0, v5
	v_min_u32_e32 v0, v0, v5
	v_max_u32_e32 v5, v1, v8
	v_min_u32_e32 v1, v1, v8
	v_max_u32_e32 v8, v7, v9
	v_min_u32_e32 v7, v7, v9
	v_max_u32_e32 v9, v14, v12
	v_min_u32_e32 v12, v14, v12
	v_max_u32_e32 v14, v2, v10
	v_min_u32_e32 v2, v2, v10
	v_max_u32_e32 v10, v3, v4
	v_min_u32_e32 v3, v3, v4
	v_max_u32_e32 v4, v11, v6
	v_min_u32_e32 v6, v11, v6
	v_max_u32_e32 v11, v15, v9
	v_min_u32_e32 v9, v15, v9
	v_max_u32_e32 v15, v16, v14
	v_min_u32_e32 v14, v16, v14
	v_max_u32_e32 v16, v5, v10
	v_min_u32_e32 v5, v5, v10
	v_max_u32_e32 v10, v8, v4
	v_min_u32_e32 v4, v8, v4
	v_max_u32_e32 v8, v13, v12
	v_min_u32_e32 v12, v13, v12
	v_max_u32_e32 v13, v0, v2
	v_min_u32_e32 v0, v0, v2
	v_max_u32_e32 v2, v1, v3
	v_min_u32_e32 v1, v1, v3
	v_max_u32_e32 v3, v7, v6
	v_min_u32_e32 v6, v7, v6
	v_max_u32_e32 v7, v11, v16
	v_min_u32_e32 v11, v11, v16
	v_max_u32_e32 v16, v15, v10
	v_min_u32_e32 v10, v15, v10
	v_max_u32_e32 v15, v9, v5
	v_min_u32_e32 v5, v9, v5
	v_max_u32_e32 v9, v14, v4
	v_min_u32_e32 v4, v14, v4
	v_max_u32_e32 v14, v8, v2
	v_min_u32_e32 v2, v8, v2
	v_max_u32_e32 v8, v13, v3
	v_min_u32_e32 v3, v13, v3
	v_max_u32_e32 v13, v12, v1
	v_min_u32_e32 v1, v12, v1
	v_max_u32_e32 v12, v0, v6
	v_min_u32_e32 v0, v0, v6
	v_max_u32_e32 v6, v7, v16
	v_min_u32_e32 v7, v7, v16
	v_max_u32_e32 v16, v11, v10
	v_min_u32_e32 v10, v11, v10
	v_max_u32_e32 v11, v15, v9
	v_min_u32_e32 v9, v15, v9
	v_max_u32_e32 v15, v5, v4
	v_min_u32_e32 v4, v5, v4
	v_max_u32_e32 v5, v14, v8
	v_min_u32_e32 v8, v14, v8
	v_max_u32_e32 v14, v2, v3
	v_min_u32_e32 v2, v2, v3
	v_max_u32_e32 v3, v13, v12
	v_min_u32_e32 v12, v13, v12
	v_max_u32_e32 v13, v1, v0
	v_min_u32_e32 v0, v1, v0
	ds_bpermute_b32 v1, v162, v6
	ds_bpermute_b32 v17, v162, v7
	ds_bpermute_b32 v18, v162, v16
	ds_bpermute_b32 v19, v162, v10
	ds_bpermute_b32 v20, v162, v11
	ds_bpermute_b32 v21, v162, v9
	ds_bpermute_b32 v22, v162, v15
	ds_bpermute_b32 v23, v162, v4
	ds_bpermute_b32 v24, v162, v5
	ds_bpermute_b32 v25, v162, v8
	ds_bpermute_b32 v26, v162, v14
	ds_bpermute_b32 v27, v162, v2
	ds_bpermute_b32 v28, v162, v3
	ds_bpermute_b32 v29, v162, v12
	ds_bpermute_b32 v30, v162, v13
	ds_bpermute_b32 v31, v162, v0
	s_waitcnt lgkmcnt(4)
; DEV unsigned xor32_u(unsigned v) { return (unsigned)__shfl_xor((int)v, 32, 64); }
; __device__ void peer_q_topk_item(const Params& P, int l, int item, char* smem) {
;     ...
;     {
;       unsigned oth[16];
; #pragma unroll
;       for (int i = 0; i < 16; ++i) oth[i] = xor32_u(Lc[i]);
;       merge_top16(Lc, oth);
;     }
; #pragma unroll
;     for (int i = 0; i < 16; ++i) { L0[i] = L1[i]; L1[i] = Lc[i]; }
;   }
	v_max_u32_e32 v11, v11, v27
	s_waitcnt lgkmcnt(3)
	v_max_u32_e32 v10, v10, v28
	s_waitcnt lgkmcnt(2)
	v_max_u32_e32 v16, v16, v29
	s_waitcnt lgkmcnt(1)
	v_max_u32_e32 v7, v7, v30
	s_waitcnt lgkmcnt(0)
	v_max_u32_e32 v6, v6, v31
	v_max_u32_e32 v9, v9, v26
	v_max_u32_e32 v15, v15, v25
	v_max_u32_e32 v4, v4, v24
	v_max_u32_e32 v5, v5, v23
	v_max_u32_e32 v8, v8, v22
	v_max_u32_e32 v14, v14, v21
	v_max_u32_e32 v2, v2, v20
	v_max_u32_e32 v3, v3, v19
	v_max_u32_e32 v12, v12, v18
	v_max_u32_e32 v13, v13, v17
	v_max_u32_e32 v0, v0, v1
	v_max_u32_e32 v1, v6, v5
	v_min_u32_e32 v5, v6, v5
	v_max_u32_e32 v6, v7, v8
	v_min_u32_e32 v7, v7, v8
	v_max_u32_e32 v8, v16, v14
	v_min_u32_e32 v14, v16, v14
	v_max_u32_e32 v16, v10, v2
	v_min_u32_e32 v2, v10, v2
	v_max_u32_e32 v10, v11, v3
	v_min_u32_e32 v3, v11, v3
	v_max_u32_e32 v11, v9, v12
	v_min_u32_e32 v9, v9, v12
	v_max_u32_e32 v12, v15, v13
	v_min_u32_e32 v13, v15, v13
	v_max_u32_e32 v15, v4, v0
	v_min_u32_e32 v0, v4, v0
	v_max_u32_e32 v4, v1, v10
	v_min_u32_e32 v1, v1, v10
	v_max_u32_e32 v10, v6, v11
	v_min_u32_e32 v6, v6, v11
	v_max_u32_e32 v11, v8, v12
	v_min_u32_e32 v8, v8, v12
	v_max_u32_e32 v12, v16, v15
	v_min_u32_e32 v15, v16, v15
	v_max_u32_e32 v16, v5, v3
	v_min_u32_e32 v3, v5, v3
	v_max_u32_e32 v5, v7, v9
	v_min_u32_e32 v7, v7, v9
	v_max_u32_e32 v9, v14, v13
	v_min_u32_e32 v13, v14, v13
	v_max_u32_e32 v14, v2, v0
	v_min_u32_e32 v0, v2, v0
	v_max_u32_e32 v2, v4, v11
	v_min_u32_e32 v4, v4, v11
	v_max_u32_e32 v11, v10, v12
	v_min_u32_e32 v10, v10, v12
	v_max_u32_e32 v12, v1, v8
	v_min_u32_e32 v8, v1, v8
	v_max_u32_e32 v17, v6, v15
	v_min_u32_e32 v6, v6, v15
	v_max_u32_e32 v15, v16, v9
	v_min_u32_e32 v9, v16, v9
	v_max_u32_e32 v18, v5, v14
	v_min_u32_e32 v5, v5, v14
	v_max_u32_e32 v19, v3, v13
	v_min_u32_e32 v20, v3, v13
	v_max_u32_e32 v21, v7, v0
	v_min_u32_e32 v22, v7, v0
	v_max_u32_e32 v16, v2, v11
	v_min_u32_e32 v3, v2, v11
	v_max_u32_e32 v0, v4, v10
	v_min_u32_e32 v10, v4, v10
	v_max_u32_e32 v1, v12, v17
	v_min_u32_e32 v11, v12, v17
	v_max_u32_e32 v12, v8, v6
	v_min_u32_e32 v13, v8, v6
	v_max_u32_e32 v14, v15, v18
	v_min_u32_e32 v2, v15, v18
	v_max_u32_e32 v7, v9, v5
	v_min_u32_e32 v4, v9, v5
	v_max_u32_e32 v8, v19, v21
	v_min_u32_e32 v5, v19, v21
	v_max_u32_e32 v15, v20, v22
	v_min_u32_e32 v6, v20, v22
	s_mov_b64 s[38:39], 0
	s_and_b64 vcc, exec, s[0:1]
	s_cbranch_vccnz .LBB0_49
	v_mov_b32_e32 v119, v15
	v_mov_b32_e32 v115, v6
	v_mov_b32_e32 v101, v14
	v_mov_b32_e32 v103, v2
	v_mov_b32_e32 v96, v4
	v_mov_b32_e32 v97, v7
	v_mov_b32_e32 v107, v8
	v_mov_b32_e32 v111, v5
	v_mov_b32_e32 v158, v16
	v_mov_b32_e32 v168, v3
	v_mov_b32_e32 v165, v0
	v_mov_b32_e32 v155, v10
	v_mov_b32_e32 v123, v1
	v_mov_b32_e32 v131, v11
	v_mov_b32_e32 v135, v12
	v_mov_b32_e32 v127, v13
	s_branch .LBB0_45
